# phase 0: conv staging 8 loads in flight, silu staging 17 loads in flight, adaLN GEMV with 32 weight loads in flight per trip and LDS reads 2 k ahead (same FMA order)
# speedup vs baseline: 1.0304x; 1.0245x over previous
.LBB0_7:
	s_cmpk_gt_i32 s44, 0xbf
	s_mov_b64 s[0:1], -1
	s_cbranch_scc0 .LBB0_11
	s_cmpk_lg_i32 s44, 0xc0
	s_cbranch_scc0 .LBB0_26
	s_add_i32 s1, s44, 0xffffff3f
	s_lshl_b32 s0, s1, 6
	s_and_b32 s45, s0, 0x3c0
	s_add_i32 s12, s45, s62
	s_lshl_b32 s47, s1, 2
	s_add_i32 s4, s12, 8
	s_add_i32 s2, s12, 16
	s_add_i32 s0, s12, 24
	s_cmpk_gt_u32 s1, 0x2ff
	s_cbranch_scc0 .LBB0_23
	s_and_b32 s46, s47, 0x3c0
	v_readlane_b32 s48, v239, 0
	s_lshl_b32 s6, s46, 2
	v_readlane_b32 s60, v239, 12
	v_readlane_b32 s61, v239, 13
	s_add_u32 s6, s60, s6
	s_addc_u32 s7, s61, 0
	v_mov_b32_e32 v7, v3
	v_lshl_add_u64 v[14:15], s[6:7], 0, v[6:7]
	s_lshl_b64 s[6:7], s[12:13], 12
	v_lshl_add_u64 v[16:17], v[14:15], 0, s[6:7]
	s_barrier
	global_load_dword v240, v[16:17], off
	s_mov_b32 s5, s13
	s_lshl_b64 s[6:7], s[4:5], 12
	v_lshl_add_u64 v[16:17], v[14:15], 0, s[6:7]
	s_mov_b32 s3, s13
	s_lshl_b64 s[6:7], s[2:3], 12
	s_mov_b32 s1, s13
	v_readlane_b32 s49, v239, 1
	v_readlane_b32 s50, v239, 2
	v_readlane_b32 s51, v239, 3
	v_readlane_b32 s52, v239, 4
	v_readlane_b32 s53, v239, 5
	v_readlane_b32 s54, v239, 6
	v_readlane_b32 s55, v239, 7
	v_readlane_b32 s56, v239, 8
	v_readlane_b32 s57, v239, 9
	v_readlane_b32 s58, v239, 10
	v_readlane_b32 s59, v239, 11
	v_readlane_b32 s62, v239, 14
	v_readlane_b32 s63, v239, 15
	v_readlane_b32 s48, v239, 16
	v_readlane_b32 s62, v239, 30
	v_readlane_b32 s63, v239, 31
	v_readlane_b32 s49, v239, 17
	v_readlane_b32 s50, v239, 18
	v_readlane_b32 s51, v239, 19
	v_readlane_b32 s52, v239, 20
	v_readlane_b32 s53, v239, 21
	v_readlane_b32 s54, v239, 22
	v_readlane_b32 s55, v239, 23
	v_readlane_b32 s56, v239, 24
	v_readlane_b32 s57, v239, 25
	v_readlane_b32 s58, v239, 26
	v_readlane_b32 s59, v239, 27
	v_readlane_b32 s60, v239, 28
	v_readlane_b32 s61, v239, 29
	s_mov_b64 s[8:9], s[62:63]
	global_load_dword v241, v[16:17], off
	v_lshl_add_u64 v[16:17], v[14:15], 0, s[6:7]
	s_lshl_b64 s[6:7], s[0:1], 12
	global_load_dword v242, v[16:17], off
	v_lshl_add_u64 v[16:17], v[14:15], 0, s[6:7]
	s_add_i32 s6, s45, s11
	s_mov_b32 s7, s13
	s_lshl_b64 s[6:7], s[6:7], 12
	global_load_dword v243, v[16:17], off
	v_lshl_add_u64 v[16:17], v[14:15], 0, s[6:7]
	s_add_i32 s6, s45, s33
	s_mov_b32 s7, s13
	s_lshl_b64 s[6:7], s[6:7], 12
	global_load_dword v244, v[16:17], off
	v_lshl_add_u64 v[16:17], v[14:15], 0, s[6:7]
	s_add_i32 s6, s45, s34
	s_mov_b32 s7, s13
	s_lshl_b64 s[6:7], s[6:7], 12
	global_load_dword v245, v[16:17], off
	v_lshl_add_u64 v[16:17], v[14:15], 0, s[6:7]
	s_add_i32 s6, s45, s35
	s_mov_b32 s7, s13
	s_lshl_b64 s[6:7], s[6:7], 12
	v_lshl_add_u64 v[14:15], v[14:15], 0, s[6:7]
	global_load_dword v246, v[16:17], off
	global_load_dword v247, v[14:15], off
	s_waitcnt vmcnt(7)
	ds_write_b32 v37, v240
	s_waitcnt vmcnt(6)
	ds_write_b32 v37, v241 offset:2080
	s_waitcnt vmcnt(5)
	ds_write_b32 v37, v242 offset:4160
	s_waitcnt vmcnt(4)
	ds_write_b32 v37, v243 offset:6240
	s_waitcnt vmcnt(3)
	ds_write_b32 v37, v244 offset:8320
	s_waitcnt vmcnt(2)
	ds_write_b32 v37, v245 offset:10400
	s_waitcnt vmcnt(1)
	ds_write_b32 v37, v246 offset:12480
	s_waitcnt vmcnt(0)
	ds_write_b32 v37, v247 offset:14560
	s_waitcnt lgkmcnt(0)
	s_barrier
	s_cbranch_execz .LBB0_24
	s_branch .LBB0_25

.LBB0_16:
	s_movk_i32 s4, 0x50
	v_and_b32_e32 v12, 0x3ff, v7
	v_ashrrev_i32_e32 v11, 10, v7
	v_lshlrev_b32_e32 v2, 2, v12
	v_cmp_gt_i32_e32 vcc, 16, v11
	v_lshl_add_u64 v[16:17], s[70:71], 0, v[2:3]
	v_lshlrev_b32_e32 v11, 2, v11
	v_cndmask_b32_e32 v17, v17, v15, vcc
	v_cndmask_b32_e32 v16, v16, v14, vcc
	global_load_dword v80, v[16:17], off
	v_mad_u32_u24 v100, v12, s4, v11
	v_lshl_add_u64 v[14:15], v[14:15], 0, s[94:95]
	v_add_u32_e32 v7, 0x200, v7
	v_and_b32_e32 v12, 0x3ff, v7
	v_ashrrev_i32_e32 v11, 10, v7
	v_lshlrev_b32_e32 v2, 2, v12
	v_cmp_gt_i32_e32 vcc, 16, v11
	v_lshl_add_u64 v[16:17], s[70:71], 0, v[2:3]
	v_lshlrev_b32_e32 v11, 2, v11
	v_cndmask_b32_e32 v17, v17, v15, vcc
	v_cndmask_b32_e32 v16, v16, v14, vcc
	global_load_dword v81, v[16:17], off
	v_mad_u32_u24 v101, v12, s4, v11
	v_lshl_add_u64 v[14:15], v[14:15], 0, s[94:95]
	v_add_u32_e32 v7, 0x200, v7
	v_and_b32_e32 v12, 0x3ff, v7
	v_ashrrev_i32_e32 v11, 10, v7
	v_lshlrev_b32_e32 v2, 2, v12
	v_cmp_gt_i32_e32 vcc, 16, v11
	v_lshl_add_u64 v[16:17], s[70:71], 0, v[2:3]
	v_lshlrev_b32_e32 v11, 2, v11
	v_cndmask_b32_e32 v17, v17, v15, vcc
	v_cndmask_b32_e32 v16, v16, v14, vcc
	global_load_dword v82, v[16:17], off
	v_mad_u32_u24 v102, v12, s4, v11
	v_lshl_add_u64 v[14:15], v[14:15], 0, s[94:95]
	v_add_u32_e32 v7, 0x200, v7
	v_and_b32_e32 v12, 0x3ff, v7
	v_ashrrev_i32_e32 v11, 10, v7
	v_lshlrev_b32_e32 v2, 2, v12
	v_cmp_gt_i32_e32 vcc, 16, v11
	v_lshl_add_u64 v[16:17], s[70:71], 0, v[2:3]
	v_lshlrev_b32_e32 v11, 2, v11
	v_cndmask_b32_e32 v17, v17, v15, vcc
	v_cndmask_b32_e32 v16, v16, v14, vcc
	global_load_dword v83, v[16:17], off
	v_mad_u32_u24 v103, v12, s4, v11
	v_lshl_add_u64 v[14:15], v[14:15], 0, s[94:95]
	v_add_u32_e32 v7, 0x200, v7
	v_and_b32_e32 v12, 0x3ff, v7
	v_ashrrev_i32_e32 v11, 10, v7
	v_lshlrev_b32_e32 v2, 2, v12
	v_cmp_gt_i32_e32 vcc, 16, v11
	v_lshl_add_u64 v[16:17], s[70:71], 0, v[2:3]
	v_lshlrev_b32_e32 v11, 2, v11
	v_cndmask_b32_e32 v17, v17, v15, vcc
	v_cndmask_b32_e32 v16, v16, v14, vcc
	global_load_dword v84, v[16:17], off
	v_mad_u32_u24 v104, v12, s4, v11
	v_lshl_add_u64 v[14:15], v[14:15], 0, s[94:95]
	v_add_u32_e32 v7, 0x200, v7
	v_and_b32_e32 v12, 0x3ff, v7
	v_ashrrev_i32_e32 v11, 10, v7
	v_lshlrev_b32_e32 v2, 2, v12
	v_cmp_gt_i32_e32 vcc, 16, v11
	v_lshl_add_u64 v[16:17], s[70:71], 0, v[2:3]
	v_lshlrev_b32_e32 v11, 2, v11
	v_cndmask_b32_e32 v17, v17, v15, vcc
	v_cndmask_b32_e32 v16, v16, v14, vcc
	global_load_dword v85, v[16:17], off
	v_mad_u32_u24 v105, v12, s4, v11
	v_lshl_add_u64 v[14:15], v[14:15], 0, s[94:95]
	v_add_u32_e32 v7, 0x200, v7
	v_and_b32_e32 v12, 0x3ff, v7
	v_ashrrev_i32_e32 v11, 10, v7
	v_lshlrev_b32_e32 v2, 2, v12
	v_cmp_gt_i32_e32 vcc, 16, v11
	v_lshl_add_u64 v[16:17], s[70:71], 0, v[2:3]
	v_lshlrev_b32_e32 v11, 2, v11
	v_cndmask_b32_e32 v17, v17, v15, vcc
	v_cndmask_b32_e32 v16, v16, v14, vcc
	global_load_dword v86, v[16:17], off
	v_mad_u32_u24 v106, v12, s4, v11
	v_lshl_add_u64 v[14:15], v[14:15], 0, s[94:95]
	v_add_u32_e32 v7, 0x200, v7
	v_and_b32_e32 v12, 0x3ff, v7
	v_ashrrev_i32_e32 v11, 10, v7
	v_lshlrev_b32_e32 v2, 2, v12
	v_cmp_gt_i32_e32 vcc, 16, v11
	v_lshl_add_u64 v[16:17], s[70:71], 0, v[2:3]
	v_lshlrev_b32_e32 v11, 2, v11
	v_cndmask_b32_e32 v17, v17, v15, vcc
	v_cndmask_b32_e32 v16, v16, v14, vcc
	global_load_dword v87, v[16:17], off
	v_mad_u32_u24 v107, v12, s4, v11
	v_lshl_add_u64 v[14:15], v[14:15], 0, s[94:95]
	v_add_u32_e32 v7, 0x200, v7
	v_and_b32_e32 v12, 0x3ff, v7
	v_ashrrev_i32_e32 v11, 10, v7
	v_lshlrev_b32_e32 v2, 2, v12
	v_cmp_gt_i32_e32 vcc, 16, v11
	v_lshl_add_u64 v[16:17], s[70:71], 0, v[2:3]
	v_lshlrev_b32_e32 v11, 2, v11
	v_cndmask_b32_e32 v17, v17, v15, vcc
	v_cndmask_b32_e32 v16, v16, v14, vcc
	global_load_dword v88, v[16:17], off
	v_mad_u32_u24 v108, v12, s4, v11
	v_lshl_add_u64 v[14:15], v[14:15], 0, s[94:95]
	v_add_u32_e32 v7, 0x200, v7
	v_and_b32_e32 v12, 0x3ff, v7
	v_ashrrev_i32_e32 v11, 10, v7
	v_lshlrev_b32_e32 v2, 2, v12
	v_cmp_gt_i32_e32 vcc, 16, v11
	v_lshl_add_u64 v[16:17], s[70:71], 0, v[2:3]
	v_lshlrev_b32_e32 v11, 2, v11
	v_cndmask_b32_e32 v17, v17, v15, vcc
	v_cndmask_b32_e32 v16, v16, v14, vcc
	global_load_dword v89, v[16:17], off
	v_mad_u32_u24 v109, v12, s4, v11
	v_lshl_add_u64 v[14:15], v[14:15], 0, s[94:95]
	v_add_u32_e32 v7, 0x200, v7
	v_and_b32_e32 v12, 0x3ff, v7
	v_ashrrev_i32_e32 v11, 10, v7
	v_lshlrev_b32_e32 v2, 2, v12
	v_cmp_gt_i32_e32 vcc, 16, v11
	v_lshl_add_u64 v[16:17], s[70:71], 0, v[2:3]
	v_lshlrev_b32_e32 v11, 2, v11
	v_cndmask_b32_e32 v17, v17, v15, vcc
	v_cndmask_b32_e32 v16, v16, v14, vcc
	global_load_dword v90, v[16:17], off
	v_mad_u32_u24 v110, v12, s4, v11
	v_lshl_add_u64 v[14:15], v[14:15], 0, s[94:95]
	v_add_u32_e32 v7, 0x200, v7
	v_and_b32_e32 v12, 0x3ff, v7
	v_ashrrev_i32_e32 v11, 10, v7
	v_lshlrev_b32_e32 v2, 2, v12
	v_cmp_gt_i32_e32 vcc, 16, v11
	v_lshl_add_u64 v[16:17], s[70:71], 0, v[2:3]
	v_lshlrev_b32_e32 v11, 2, v11
	v_cndmask_b32_e32 v17, v17, v15, vcc
	v_cndmask_b32_e32 v16, v16, v14, vcc
	global_load_dword v91, v[16:17], off
	v_mad_u32_u24 v111, v12, s4, v11
	v_lshl_add_u64 v[14:15], v[14:15], 0, s[94:95]
	v_add_u32_e32 v7, 0x200, v7
	v_and_b32_e32 v12, 0x3ff, v7
	v_ashrrev_i32_e32 v11, 10, v7
	v_lshlrev_b32_e32 v2, 2, v12
	v_cmp_gt_i32_e32 vcc, 16, v11
	v_lshl_add_u64 v[16:17], s[70:71], 0, v[2:3]
	v_lshlrev_b32_e32 v11, 2, v11
	v_cndmask_b32_e32 v17, v17, v15, vcc
	v_cndmask_b32_e32 v16, v16, v14, vcc
	global_load_dword v92, v[16:17], off
	v_mad_u32_u24 v112, v12, s4, v11
	v_lshl_add_u64 v[14:15], v[14:15], 0, s[94:95]
	v_add_u32_e32 v7, 0x200, v7
	v_and_b32_e32 v12, 0x3ff, v7
	v_ashrrev_i32_e32 v11, 10, v7
	v_lshlrev_b32_e32 v2, 2, v12
	v_cmp_gt_i32_e32 vcc, 16, v11
	v_lshl_add_u64 v[16:17], s[70:71], 0, v[2:3]
	v_lshlrev_b32_e32 v11, 2, v11
	v_cndmask_b32_e32 v17, v17, v15, vcc
	v_cndmask_b32_e32 v16, v16, v14, vcc
	global_load_dword v93, v[16:17], off
	v_mad_u32_u24 v113, v12, s4, v11
	v_lshl_add_u64 v[14:15], v[14:15], 0, s[94:95]
	v_add_u32_e32 v7, 0x200, v7
	v_and_b32_e32 v12, 0x3ff, v7
	v_ashrrev_i32_e32 v11, 10, v7
	v_lshlrev_b32_e32 v2, 2, v12
	v_cmp_gt_i32_e32 vcc, 16, v11
	v_lshl_add_u64 v[16:17], s[70:71], 0, v[2:3]
	v_lshlrev_b32_e32 v11, 2, v11
	v_cndmask_b32_e32 v17, v17, v15, vcc
	v_cndmask_b32_e32 v16, v16, v14, vcc
	global_load_dword v94, v[16:17], off
	v_mad_u32_u24 v114, v12, s4, v11
	v_lshl_add_u64 v[14:15], v[14:15], 0, s[94:95]
	v_add_u32_e32 v7, 0x200, v7
	v_and_b32_e32 v12, 0x3ff, v7
	v_ashrrev_i32_e32 v11, 10, v7
	v_lshlrev_b32_e32 v2, 2, v12
	v_cmp_gt_i32_e32 vcc, 16, v11
	v_lshl_add_u64 v[16:17], s[70:71], 0, v[2:3]
	v_lshlrev_b32_e32 v11, 2, v11
	v_cndmask_b32_e32 v17, v17, v15, vcc
	v_cndmask_b32_e32 v16, v16, v14, vcc
	global_load_dword v95, v[16:17], off
	v_mad_u32_u24 v115, v12, s4, v11
	v_lshl_add_u64 v[14:15], v[14:15], 0, s[94:95]
	v_add_u32_e32 v7, 0x200, v7
	v_and_b32_e32 v12, 0x3ff, v7
	v_ashrrev_i32_e32 v11, 10, v7
	v_lshlrev_b32_e32 v2, 2, v12
	v_cmp_gt_i32_e32 vcc, 16, v11
	v_lshl_add_u64 v[16:17], s[70:71], 0, v[2:3]
	v_lshlrev_b32_e32 v11, 2, v11
	v_cndmask_b32_e32 v17, v17, v15, vcc
	v_cndmask_b32_e32 v16, v16, v14, vcc
	global_load_dword v96, v[16:17], off
	v_mad_u32_u24 v116, v12, s4, v11
	v_lshl_add_u64 v[14:15], v[14:15], 0, s[94:95]
	v_add_u32_e32 v7, 0x200, v7
	s_waitcnt vmcnt(16)
	v_mul_f32_e32 v16, 0xbfb8aa3b, v80
	v_exp_f32_e32 v16, v16
	s_nop 0
	v_add_f32_e32 v16, 1.0, v16
	v_rcp_f32_e32 v16, v16
	s_nop 0
	v_mul_f32_e32 v2, v80, v16
	ds_write_b32 v100, v2
	s_waitcnt vmcnt(15)
	v_mul_f32_e32 v16, 0xbfb8aa3b, v81
	v_exp_f32_e32 v16, v16
	s_nop 0
	v_add_f32_e32 v16, 1.0, v16
	v_rcp_f32_e32 v16, v16
	s_nop 0
	v_mul_f32_e32 v2, v81, v16
	ds_write_b32 v101, v2
	s_waitcnt vmcnt(14)
	v_mul_f32_e32 v16, 0xbfb8aa3b, v82
	v_exp_f32_e32 v16, v16
	s_nop 0
	v_add_f32_e32 v16, 1.0, v16
	v_rcp_f32_e32 v16, v16
	s_nop 0
	v_mul_f32_e32 v2, v82, v16
	ds_write_b32 v102, v2
	s_waitcnt vmcnt(13)
	v_mul_f32_e32 v16, 0xbfb8aa3b, v83
	v_exp_f32_e32 v16, v16
	s_nop 0
	v_add_f32_e32 v16, 1.0, v16
	v_rcp_f32_e32 v16, v16
	s_nop 0
	v_mul_f32_e32 v2, v83, v16
	ds_write_b32 v103, v2
	s_waitcnt vmcnt(12)
	v_mul_f32_e32 v16, 0xbfb8aa3b, v84
	v_exp_f32_e32 v16, v16
	s_nop 0
	v_add_f32_e32 v16, 1.0, v16
	v_rcp_f32_e32 v16, v16
	s_nop 0
	v_mul_f32_e32 v2, v84, v16
	ds_write_b32 v104, v2
	s_waitcnt vmcnt(11)
	v_mul_f32_e32 v16, 0xbfb8aa3b, v85
	v_exp_f32_e32 v16, v16
	s_nop 0
	v_add_f32_e32 v16, 1.0, v16
	v_rcp_f32_e32 v16, v16
	s_nop 0
	v_mul_f32_e32 v2, v85, v16
	ds_write_b32 v105, v2
	s_waitcnt vmcnt(10)
	v_mul_f32_e32 v16, 0xbfb8aa3b, v86
	v_exp_f32_e32 v16, v16
	s_nop 0
	v_add_f32_e32 v16, 1.0, v16
	v_rcp_f32_e32 v16, v16
	s_nop 0
	v_mul_f32_e32 v2, v86, v16
	ds_write_b32 v106, v2
	s_waitcnt vmcnt(9)
	v_mul_f32_e32 v16, 0xbfb8aa3b, v87
	v_exp_f32_e32 v16, v16
	s_nop 0
	v_add_f32_e32 v16, 1.0, v16
	v_rcp_f32_e32 v16, v16
	s_nop 0
	v_mul_f32_e32 v2, v87, v16
	ds_write_b32 v107, v2
	s_waitcnt vmcnt(8)
	v_mul_f32_e32 v16, 0xbfb8aa3b, v88
	v_exp_f32_e32 v16, v16
	s_nop 0
	v_add_f32_e32 v16, 1.0, v16
	v_rcp_f32_e32 v16, v16
	s_nop 0
	v_mul_f32_e32 v2, v88, v16
	ds_write_b32 v108, v2
	s_waitcnt vmcnt(7)
	v_mul_f32_e32 v16, 0xbfb8aa3b, v89
	v_exp_f32_e32 v16, v16
	s_nop 0
	v_add_f32_e32 v16, 1.0, v16
	v_rcp_f32_e32 v16, v16
	s_nop 0
	v_mul_f32_e32 v2, v89, v16
	ds_write_b32 v109, v2
	s_waitcnt vmcnt(6)
	v_mul_f32_e32 v16, 0xbfb8aa3b, v90
	v_exp_f32_e32 v16, v16
	s_nop 0
	v_add_f32_e32 v16, 1.0, v16
	v_rcp_f32_e32 v16, v16
	s_nop 0
	v_mul_f32_e32 v2, v90, v16
	ds_write_b32 v110, v2
	s_waitcnt vmcnt(5)
	v_mul_f32_e32 v16, 0xbfb8aa3b, v91
	v_exp_f32_e32 v16, v16
	s_nop 0
	v_add_f32_e32 v16, 1.0, v16
	v_rcp_f32_e32 v16, v16
	s_nop 0
	v_mul_f32_e32 v2, v91, v16
	ds_write_b32 v111, v2
	s_waitcnt vmcnt(4)
	v_mul_f32_e32 v16, 0xbfb8aa3b, v92
	v_exp_f32_e32 v16, v16
	s_nop 0
	v_add_f32_e32 v16, 1.0, v16
	v_rcp_f32_e32 v16, v16
	s_nop 0
	v_mul_f32_e32 v2, v92, v16
	ds_write_b32 v112, v2
	s_waitcnt vmcnt(3)
	v_mul_f32_e32 v16, 0xbfb8aa3b, v93
	v_exp_f32_e32 v16, v16
	s_nop 0
	v_add_f32_e32 v16, 1.0, v16
	v_rcp_f32_e32 v16, v16
	s_nop 0
	v_mul_f32_e32 v2, v93, v16
	ds_write_b32 v113, v2
	s_waitcnt vmcnt(2)
	v_mul_f32_e32 v16, 0xbfb8aa3b, v94
	v_exp_f32_e32 v16, v16
	s_nop 0
	v_add_f32_e32 v16, 1.0, v16
	v_rcp_f32_e32 v16, v16
	s_nop 0
	v_mul_f32_e32 v2, v94, v16
	ds_write_b32 v114, v2
	s_waitcnt vmcnt(1)
	v_mul_f32_e32 v16, 0xbfb8aa3b, v95
	v_exp_f32_e32 v16, v16
	s_nop 0
	v_add_f32_e32 v16, 1.0, v16
	v_rcp_f32_e32 v16, v16
	s_nop 0
	v_mul_f32_e32 v2, v95, v16
	ds_write_b32 v115, v2
	s_waitcnt vmcnt(0)
	v_mul_f32_e32 v16, 0xbfb8aa3b, v96
	v_exp_f32_e32 v16, v16
	s_nop 0
	v_add_f32_e32 v16, 1.0, v16
	v_rcp_f32_e32 v16, v16
	s_nop 0
	v_mul_f32_e32 v2, v96, v16
	ds_write_b32 v116, v2
	s_movk_i32 s4, 0x43ff
	v_cmp_lt_i32_e32 vcc, s4, v7
	s_cbranch_vccz .LBB0_16

.LBB0_19:
	s_mul_i32 s12, s1, 0x1800
	v_lshl_add_u64 v[32:33], s[12:13], 2, v[14:15]
	s_add_i32 s3, s1, s36
	s_mulk_i32 s3, 0x50
	v_mov_b32_e32 v5, s3
	s_add_i32 s1, s1, 32
	s_mov_b32 s6, 0x6000
	s_mov_b32 s7, 0
	ds_read_b128 v[144:147], v5
	ds_read_b128 v[148:151], v5 offset:16
	ds_read_b128 v[152:155], v5 offset:32
	ds_read_b128 v[156:159], v5 offset:48
	ds_read_b32 v192, v5 offset:64
	ds_read_b128 v[160:163], v5 offset:80
	ds_read_b128 v[164:167], v5 offset:96
	ds_read_b128 v[168:171], v5 offset:112
	ds_read_b128 v[172:175], v5 offset:128
	ds_read_b32 v193, v5 offset:144
	global_load_dword v80, v[32:33], off
	v_lshl_add_u64 v[32:33], v[32:33], 0, s[6:7]
	global_load_dword v82, v[32:33], off
	v_lshl_add_u64 v[32:33], v[32:33], 0, s[6:7]
	global_load_dword v84, v[32:33], off
	v_lshl_add_u64 v[32:33], v[32:33], 0, s[6:7]
	global_load_dword v86, v[32:33], off
	v_lshl_add_u64 v[32:33], v[32:33], 0, s[6:7]
	global_load_dword v88, v[32:33], off
	v_lshl_add_u64 v[32:33], v[32:33], 0, s[6:7]
	global_load_dword v90, v[32:33], off
	v_lshl_add_u64 v[32:33], v[32:33], 0, s[6:7]
	global_load_dword v92, v[32:33], off
	v_lshl_add_u64 v[32:33], v[32:33], 0, s[6:7]
	global_load_dword v94, v[32:33], off
	v_lshl_add_u64 v[32:33], v[32:33], 0, s[6:7]
	global_load_dword v96, v[32:33], off
	v_lshl_add_u64 v[32:33], v[32:33], 0, s[6:7]
	global_load_dword v98, v[32:33], off
	v_lshl_add_u64 v[32:33], v[32:33], 0, s[6:7]
	global_load_dword v100, v[32:33], off
	v_lshl_add_u64 v[32:33], v[32:33], 0, s[6:7]
	global_load_dword v102, v[32:33], off
	v_lshl_add_u64 v[32:33], v[32:33], 0, s[6:7]
	global_load_dword v104, v[32:33], off
	v_lshl_add_u64 v[32:33], v[32:33], 0, s[6:7]
	global_load_dword v106, v[32:33], off
	v_lshl_add_u64 v[32:33], v[32:33], 0, s[6:7]
	global_load_dword v108, v[32:33], off
	v_lshl_add_u64 v[32:33], v[32:33], 0, s[6:7]
	global_load_dword v110, v[32:33], off
	v_lshl_add_u64 v[32:33], v[32:33], 0, s[6:7]
	global_load_dword v112, v[32:33], off
	v_lshl_add_u64 v[32:33], v[32:33], 0, s[6:7]
	global_load_dword v114, v[32:33], off
	v_lshl_add_u64 v[32:33], v[32:33], 0, s[6:7]
	global_load_dword v116, v[32:33], off
	v_lshl_add_u64 v[32:33], v[32:33], 0, s[6:7]
	global_load_dword v118, v[32:33], off
	v_lshl_add_u64 v[32:33], v[32:33], 0, s[6:7]
	global_load_dword v120, v[32:33], off
	v_lshl_add_u64 v[32:33], v[32:33], 0, s[6:7]
	global_load_dword v122, v[32:33], off
	v_lshl_add_u64 v[32:33], v[32:33], 0, s[6:7]
	global_load_dword v124, v[32:33], off
	v_lshl_add_u64 v[32:33], v[32:33], 0, s[6:7]
	global_load_dword v126, v[32:33], off
	v_lshl_add_u64 v[32:33], v[32:33], 0, s[6:7]
	global_load_dword v128, v[32:33], off
	v_lshl_add_u64 v[32:33], v[32:33], 0, s[6:7]
	global_load_dword v130, v[32:33], off
	v_lshl_add_u64 v[32:33], v[32:33], 0, s[6:7]
	global_load_dword v132, v[32:33], off
	v_lshl_add_u64 v[32:33], v[32:33], 0, s[6:7]
	global_load_dword v134, v[32:33], off
	v_lshl_add_u64 v[32:33], v[32:33], 0, s[6:7]
	global_load_dword v136, v[32:33], off
	v_lshl_add_u64 v[32:33], v[32:33], 0, s[6:7]
	global_load_dword v138, v[32:33], off
	v_lshl_add_u64 v[32:33], v[32:33], 0, s[6:7]
	global_load_dword v140, v[32:33], off
	v_lshl_add_u64 v[32:33], v[32:33], 0, s[6:7]
	global_load_dword v142, v[32:33], off
	ds_read_b128 v[176:179], v5 offset:160
	ds_read_b128 v[180:183], v5 offset:176
	ds_read_b128 v[184:187], v5 offset:192
	ds_read_b128 v[188:191], v5 offset:208
	ds_read_b32 v194, v5 offset:224
	s_waitcnt vmcnt(31) lgkmcnt(10)
	v_pk_fma_f32 v[16:17], v[80:81], v[144:145], v[16:17] op_sel_hi:[0,1,1]
	v_pk_fma_f32 v[18:19], v[80:81], v[146:147], v[18:19] op_sel_hi:[0,1,1]
	v_pk_fma_f32 v[20:21], v[80:81], v[148:149], v[20:21] op_sel_hi:[0,1,1]
	v_pk_fma_f32 v[22:23], v[80:81], v[150:151], v[22:23] op_sel_hi:[0,1,1]
	v_pk_fma_f32 v[24:25], v[80:81], v[152:153], v[24:25] op_sel_hi:[0,1,1]
	v_pk_fma_f32 v[26:27], v[80:81], v[154:155], v[26:27] op_sel_hi:[0,1,1]
	v_pk_fma_f32 v[28:29], v[80:81], v[156:157], v[28:29] op_sel_hi:[0,1,1]
	v_pk_fma_f32 v[30:31], v[80:81], v[158:159], v[30:31] op_sel_hi:[0,1,1]
	v_fmac_f32_e32 v2, v80, v192
	ds_read_b128 v[144:147], v5 offset:240
	ds_read_b128 v[148:151], v5 offset:256
	ds_read_b128 v[152:155], v5 offset:272
	ds_read_b128 v[156:159], v5 offset:288
	ds_read_b32 v192, v5 offset:304
	s_waitcnt vmcnt(30) lgkmcnt(10)
	v_pk_fma_f32 v[16:17], v[82:83], v[160:161], v[16:17] op_sel_hi:[0,1,1]
	v_pk_fma_f32 v[18:19], v[82:83], v[162:163], v[18:19] op_sel_hi:[0,1,1]
	v_pk_fma_f32 v[20:21], v[82:83], v[164:165], v[20:21] op_sel_hi:[0,1,1]
	v_pk_fma_f32 v[22:23], v[82:83], v[166:167], v[22:23] op_sel_hi:[0,1,1]
	v_pk_fma_f32 v[24:25], v[82:83], v[168:169], v[24:25] op_sel_hi:[0,1,1]
	v_pk_fma_f32 v[26:27], v[82:83], v[170:171], v[26:27] op_sel_hi:[0,1,1]
	v_pk_fma_f32 v[28:29], v[82:83], v[172:173], v[28:29] op_sel_hi:[0,1,1]
	v_pk_fma_f32 v[30:31], v[82:83], v[174:175], v[30:31] op_sel_hi:[0,1,1]
	v_fmac_f32_e32 v2, v82, v193
	ds_read_b128 v[160:163], v5 offset:320
	ds_read_b128 v[164:167], v5 offset:336
	ds_read_b128 v[168:171], v5 offset:352
	ds_read_b128 v[172:175], v5 offset:368
	ds_read_b32 v193, v5 offset:384
	s_waitcnt vmcnt(29) lgkmcnt(10)
	v_pk_fma_f32 v[16:17], v[84:85], v[176:177], v[16:17] op_sel_hi:[0,1,1]
	v_pk_fma_f32 v[18:19], v[84:85], v[178:179], v[18:19] op_sel_hi:[0,1,1]
	v_pk_fma_f32 v[20:21], v[84:85], v[180:181], v[20:21] op_sel_hi:[0,1,1]
	v_pk_fma_f32 v[22:23], v[84:85], v[182:183], v[22:23] op_sel_hi:[0,1,1]
	v_pk_fma_f32 v[24:25], v[84:85], v[184:185], v[24:25] op_sel_hi:[0,1,1]
	v_pk_fma_f32 v[26:27], v[84:85], v[186:187], v[26:27] op_sel_hi:[0,1,1]
	v_pk_fma_f32 v[28:29], v[84:85], v[188:189], v[28:29] op_sel_hi:[0,1,1]
	v_pk_fma_f32 v[30:31], v[84:85], v[190:191], v[30:31] op_sel_hi:[0,1,1]
	v_fmac_f32_e32 v2, v84, v194
	ds_read_b128 v[176:179], v5 offset:400
	ds_read_b128 v[180:183], v5 offset:416
	ds_read_b128 v[184:187], v5 offset:432
	ds_read_b128 v[188:191], v5 offset:448
	ds_read_b32 v194, v5 offset:464
	s_waitcnt vmcnt(28) lgkmcnt(10)
	v_pk_fma_f32 v[16:17], v[86:87], v[144:145], v[16:17] op_sel_hi:[0,1,1]
	v_pk_fma_f32 v[18:19], v[86:87], v[146:147], v[18:19] op_sel_hi:[0,1,1]
	v_pk_fma_f32 v[20:21], v[86:87], v[148:149], v[20:21] op_sel_hi:[0,1,1]
	v_pk_fma_f32 v[22:23], v[86:87], v[150:151], v[22:23] op_sel_hi:[0,1,1]
	v_pk_fma_f32 v[24:25], v[86:87], v[152:153], v[24:25] op_sel_hi:[0,1,1]
	v_pk_fma_f32 v[26:27], v[86:87], v[154:155], v[26:27] op_sel_hi:[0,1,1]
	v_pk_fma_f32 v[28:29], v[86:87], v[156:157], v[28:29] op_sel_hi:[0,1,1]
	v_pk_fma_f32 v[30:31], v[86:87], v[158:159], v[30:31] op_sel_hi:[0,1,1]
	v_fmac_f32_e32 v2, v86, v192
	ds_read_b128 v[144:147], v5 offset:480
	ds_read_b128 v[148:151], v5 offset:496
	ds_read_b128 v[152:155], v5 offset:512
	ds_read_b128 v[156:159], v5 offset:528
	ds_read_b32 v192, v5 offset:544
	s_waitcnt vmcnt(27) lgkmcnt(10)
	v_pk_fma_f32 v[16:17], v[88:89], v[160:161], v[16:17] op_sel_hi:[0,1,1]
	v_pk_fma_f32 v[18:19], v[88:89], v[162:163], v[18:19] op_sel_hi:[0,1,1]
	v_pk_fma_f32 v[20:21], v[88:89], v[164:165], v[20:21] op_sel_hi:[0,1,1]
	v_pk_fma_f32 v[22:23], v[88:89], v[166:167], v[22:23] op_sel_hi:[0,1,1]
	v_pk_fma_f32 v[24:25], v[88:89], v[168:169], v[24:25] op_sel_hi:[0,1,1]
	v_pk_fma_f32 v[26:27], v[88:89], v[170:171], v[26:27] op_sel_hi:[0,1,1]
	v_pk_fma_f32 v[28:29], v[88:89], v[172:173], v[28:29] op_sel_hi:[0,1,1]
	v_pk_fma_f32 v[30:31], v[88:89], v[174:175], v[30:31] op_sel_hi:[0,1,1]
	v_fmac_f32_e32 v2, v88, v193
	ds_read_b128 v[160:163], v5 offset:560
	ds_read_b128 v[164:167], v5 offset:576
	ds_read_b128 v[168:171], v5 offset:592
	ds_read_b128 v[172:175], v5 offset:608
	ds_read_b32 v193, v5 offset:624
	s_waitcnt vmcnt(26) lgkmcnt(10)
	v_pk_fma_f32 v[16:17], v[90:91], v[176:177], v[16:17] op_sel_hi:[0,1,1]
	v_pk_fma_f32 v[18:19], v[90:91], v[178:179], v[18:19] op_sel_hi:[0,1,1]
	v_pk_fma_f32 v[20:21], v[90:91], v[180:181], v[20:21] op_sel_hi:[0,1,1]
	v_pk_fma_f32 v[22:23], v[90:91], v[182:183], v[22:23] op_sel_hi:[0,1,1]
	v_pk_fma_f32 v[24:25], v[90:91], v[184:185], v[24:25] op_sel_hi:[0,1,1]
	v_pk_fma_f32 v[26:27], v[90:91], v[186:187], v[26:27] op_sel_hi:[0,1,1]
	v_pk_fma_f32 v[28:29], v[90:91], v[188:189], v[28:29] op_sel_hi:[0,1,1]
	v_pk_fma_f32 v[30:31], v[90:91], v[190:191], v[30:31] op_sel_hi:[0,1,1]
	v_fmac_f32_e32 v2, v90, v194
	ds_read_b128 v[176:179], v5 offset:640
	ds_read_b128 v[180:183], v5 offset:656
	ds_read_b128 v[184:187], v5 offset:672
	ds_read_b128 v[188:191], v5 offset:688
	ds_read_b32 v194, v5 offset:704
	s_waitcnt vmcnt(25) lgkmcnt(10)
	v_pk_fma_f32 v[16:17], v[92:93], v[144:145], v[16:17] op_sel_hi:[0,1,1]
	v_pk_fma_f32 v[18:19], v[92:93], v[146:147], v[18:19] op_sel_hi:[0,1,1]
	v_pk_fma_f32 v[20:21], v[92:93], v[148:149], v[20:21] op_sel_hi:[0,1,1]
	v_pk_fma_f32 v[22:23], v[92:93], v[150:151], v[22:23] op_sel_hi:[0,1,1]
	v_pk_fma_f32 v[24:25], v[92:93], v[152:153], v[24:25] op_sel_hi:[0,1,1]
	v_pk_fma_f32 v[26:27], v[92:93], v[154:155], v[26:27] op_sel_hi:[0,1,1]
	v_pk_fma_f32 v[28:29], v[92:93], v[156:157], v[28:29] op_sel_hi:[0,1,1]
	v_pk_fma_f32 v[30:31], v[92:93], v[158:159], v[30:31] op_sel_hi:[0,1,1]
	v_fmac_f32_e32 v2, v92, v192
	ds_read_b128 v[144:147], v5 offset:720
	ds_read_b128 v[148:151], v5 offset:736
	ds_read_b128 v[152:155], v5 offset:752
	ds_read_b128 v[156:159], v5 offset:768
	ds_read_b32 v192, v5 offset:784
	s_waitcnt vmcnt(24) lgkmcnt(10)
	v_pk_fma_f32 v[16:17], v[94:95], v[160:161], v[16:17] op_sel_hi:[0,1,1]
	v_pk_fma_f32 v[18:19], v[94:95], v[162:163], v[18:19] op_sel_hi:[0,1,1]
	v_pk_fma_f32 v[20:21], v[94:95], v[164:165], v[20:21] op_sel_hi:[0,1,1]
	v_pk_fma_f32 v[22:23], v[94:95], v[166:167], v[22:23] op_sel_hi:[0,1,1]
	v_pk_fma_f32 v[24:25], v[94:95], v[168:169], v[24:25] op_sel_hi:[0,1,1]
	v_pk_fma_f32 v[26:27], v[94:95], v[170:171], v[26:27] op_sel_hi:[0,1,1]
	v_pk_fma_f32 v[28:29], v[94:95], v[172:173], v[28:29] op_sel_hi:[0,1,1]
	v_pk_fma_f32 v[30:31], v[94:95], v[174:175], v[30:31] op_sel_hi:[0,1,1]
	v_fmac_f32_e32 v2, v94, v193
	ds_read_b128 v[160:163], v5 offset:800
	ds_read_b128 v[164:167], v5 offset:816
	ds_read_b128 v[168:171], v5 offset:832
	ds_read_b128 v[172:175], v5 offset:848
	ds_read_b32 v193, v5 offset:864
	s_waitcnt vmcnt(23) lgkmcnt(10)
	v_pk_fma_f32 v[16:17], v[96:97], v[176:177], v[16:17] op_sel_hi:[0,1,1]
	v_pk_fma_f32 v[18:19], v[96:97], v[178:179], v[18:19] op_sel_hi:[0,1,1]
	v_pk_fma_f32 v[20:21], v[96:97], v[180:181], v[20:21] op_sel_hi:[0,1,1]
	v_pk_fma_f32 v[22:23], v[96:97], v[182:183], v[22:23] op_sel_hi:[0,1,1]
	v_pk_fma_f32 v[24:25], v[96:97], v[184:185], v[24:25] op_sel_hi:[0,1,1]
	v_pk_fma_f32 v[26:27], v[96:97], v[186:187], v[26:27] op_sel_hi:[0,1,1]
	v_pk_fma_f32 v[28:29], v[96:97], v[188:189], v[28:29] op_sel_hi:[0,1,1]
	v_pk_fma_f32 v[30:31], v[96:97], v[190:191], v[30:31] op_sel_hi:[0,1,1]
	v_fmac_f32_e32 v2, v96, v194
	ds_read_b128 v[176:179], v5 offset:880
	ds_read_b128 v[180:183], v5 offset:896
	ds_read_b128 v[184:187], v5 offset:912
	ds_read_b128 v[188:191], v5 offset:928
	ds_read_b32 v194, v5 offset:944
	s_waitcnt vmcnt(22) lgkmcnt(10)
	v_pk_fma_f32 v[16:17], v[98:99], v[144:145], v[16:17] op_sel_hi:[0,1,1]
	v_pk_fma_f32 v[18:19], v[98:99], v[146:147], v[18:19] op_sel_hi:[0,1,1]
	v_pk_fma_f32 v[20:21], v[98:99], v[148:149], v[20:21] op_sel_hi:[0,1,1]
	v_pk_fma_f32 v[22:23], v[98:99], v[150:151], v[22:23] op_sel_hi:[0,1,1]
	v_pk_fma_f32 v[24:25], v[98:99], v[152:153], v[24:25] op_sel_hi:[0,1,1]
	v_pk_fma_f32 v[26:27], v[98:99], v[154:155], v[26:27] op_sel_hi:[0,1,1]
	v_pk_fma_f32 v[28:29], v[98:99], v[156:157], v[28:29] op_sel_hi:[0,1,1]
	v_pk_fma_f32 v[30:31], v[98:99], v[158:159], v[30:31] op_sel_hi:[0,1,1]
	v_fmac_f32_e32 v2, v98, v192
	ds_read_b128 v[144:147], v5 offset:960
	ds_read_b128 v[148:151], v5 offset:976
	ds_read_b128 v[152:155], v5 offset:992
	ds_read_b128 v[156:159], v5 offset:1008
	ds_read_b32 v192, v5 offset:1024
	s_waitcnt vmcnt(21) lgkmcnt(10)
	v_pk_fma_f32 v[16:17], v[100:101], v[160:161], v[16:17] op_sel_hi:[0,1,1]
	v_pk_fma_f32 v[18:19], v[100:101], v[162:163], v[18:19] op_sel_hi:[0,1,1]
	v_pk_fma_f32 v[20:21], v[100:101], v[164:165], v[20:21] op_sel_hi:[0,1,1]
	v_pk_fma_f32 v[22:23], v[100:101], v[166:167], v[22:23] op_sel_hi:[0,1,1]
	v_pk_fma_f32 v[24:25], v[100:101], v[168:169], v[24:25] op_sel_hi:[0,1,1]
	v_pk_fma_f32 v[26:27], v[100:101], v[170:171], v[26:27] op_sel_hi:[0,1,1]
	v_pk_fma_f32 v[28:29], v[100:101], v[172:173], v[28:29] op_sel_hi:[0,1,1]
	v_pk_fma_f32 v[30:31], v[100:101], v[174:175], v[30:31] op_sel_hi:[0,1,1]
	v_fmac_f32_e32 v2, v100, v193
	ds_read_b128 v[160:163], v5 offset:1040
	ds_read_b128 v[164:167], v5 offset:1056
	ds_read_b128 v[168:171], v5 offset:1072
	ds_read_b128 v[172:175], v5 offset:1088
	ds_read_b32 v193, v5 offset:1104
	s_waitcnt vmcnt(20) lgkmcnt(10)
	v_pk_fma_f32 v[16:17], v[102:103], v[176:177], v[16:17] op_sel_hi:[0,1,1]
	v_pk_fma_f32 v[18:19], v[102:103], v[178:179], v[18:19] op_sel_hi:[0,1,1]
	v_pk_fma_f32 v[20:21], v[102:103], v[180:181], v[20:21] op_sel_hi:[0,1,1]
	v_pk_fma_f32 v[22:23], v[102:103], v[182:183], v[22:23] op_sel_hi:[0,1,1]
	v_pk_fma_f32 v[24:25], v[102:103], v[184:185], v[24:25] op_sel_hi:[0,1,1]
	v_pk_fma_f32 v[26:27], v[102:103], v[186:187], v[26:27] op_sel_hi:[0,1,1]
	v_pk_fma_f32 v[28:29], v[102:103], v[188:189], v[28:29] op_sel_hi:[0,1,1]
	v_pk_fma_f32 v[30:31], v[102:103], v[190:191], v[30:31] op_sel_hi:[0,1,1]
	v_fmac_f32_e32 v2, v102, v194
	ds_read_b128 v[176:179], v5 offset:1120
	ds_read_b128 v[180:183], v5 offset:1136
	ds_read_b128 v[184:187], v5 offset:1152
	ds_read_b128 v[188:191], v5 offset:1168
	ds_read_b32 v194, v5 offset:1184
	s_waitcnt vmcnt(19) lgkmcnt(10)
	v_pk_fma_f32 v[16:17], v[104:105], v[144:145], v[16:17] op_sel_hi:[0,1,1]
	v_pk_fma_f32 v[18:19], v[104:105], v[146:147], v[18:19] op_sel_hi:[0,1,1]
	v_pk_fma_f32 v[20:21], v[104:105], v[148:149], v[20:21] op_sel_hi:[0,1,1]
	v_pk_fma_f32 v[22:23], v[104:105], v[150:151], v[22:23] op_sel_hi:[0,1,1]
	v_pk_fma_f32 v[24:25], v[104:105], v[152:153], v[24:25] op_sel_hi:[0,1,1]
	v_pk_fma_f32 v[26:27], v[104:105], v[154:155], v[26:27] op_sel_hi:[0,1,1]
	v_pk_fma_f32 v[28:29], v[104:105], v[156:157], v[28:29] op_sel_hi:[0,1,1]
	v_pk_fma_f32 v[30:31], v[104:105], v[158:159], v[30:31] op_sel_hi:[0,1,1]
	v_fmac_f32_e32 v2, v104, v192
	ds_read_b128 v[144:147], v5 offset:1200
	ds_read_b128 v[148:151], v5 offset:1216
	ds_read_b128 v[152:155], v5 offset:1232
	ds_read_b128 v[156:159], v5 offset:1248
	ds_read_b32 v192, v5 offset:1264
	s_waitcnt vmcnt(18) lgkmcnt(10)
	v_pk_fma_f32 v[16:17], v[106:107], v[160:161], v[16:17] op_sel_hi:[0,1,1]
	v_pk_fma_f32 v[18:19], v[106:107], v[162:163], v[18:19] op_sel_hi:[0,1,1]
	v_pk_fma_f32 v[20:21], v[106:107], v[164:165], v[20:21] op_sel_hi:[0,1,1]
	v_pk_fma_f32 v[22:23], v[106:107], v[166:167], v[22:23] op_sel_hi:[0,1,1]
	v_pk_fma_f32 v[24:25], v[106:107], v[168:169], v[24:25] op_sel_hi:[0,1,1]
	v_pk_fma_f32 v[26:27], v[106:107], v[170:171], v[26:27] op_sel_hi:[0,1,1]
	v_pk_fma_f32 v[28:29], v[106:107], v[172:173], v[28:29] op_sel_hi:[0,1,1]
	v_pk_fma_f32 v[30:31], v[106:107], v[174:175], v[30:31] op_sel_hi:[0,1,1]
	v_fmac_f32_e32 v2, v106, v193
	ds_read_b128 v[160:163], v5 offset:1280
	ds_read_b128 v[164:167], v5 offset:1296
	ds_read_b128 v[168:171], v5 offset:1312
	ds_read_b128 v[172:175], v5 offset:1328
	ds_read_b32 v193, v5 offset:1344
	s_waitcnt vmcnt(17) lgkmcnt(10)
	v_pk_fma_f32 v[16:17], v[108:109], v[176:177], v[16:17] op_sel_hi:[0,1,1]
	v_pk_fma_f32 v[18:19], v[108:109], v[178:179], v[18:19] op_sel_hi:[0,1,1]
	v_pk_fma_f32 v[20:21], v[108:109], v[180:181], v[20:21] op_sel_hi:[0,1,1]
	v_pk_fma_f32 v[22:23], v[108:109], v[182:183], v[22:23] op_sel_hi:[0,1,1]
	v_pk_fma_f32 v[24:25], v[108:109], v[184:185], v[24:25] op_sel_hi:[0,1,1]
	v_pk_fma_f32 v[26:27], v[108:109], v[186:187], v[26:27] op_sel_hi:[0,1,1]
	v_pk_fma_f32 v[28:29], v[108:109], v[188:189], v[28:29] op_sel_hi:[0,1,1]
	v_pk_fma_f32 v[30:31], v[108:109], v[190:191], v[30:31] op_sel_hi:[0,1,1]
	v_fmac_f32_e32 v2, v108, v194
	ds_read_b128 v[176:179], v5 offset:1360
	ds_read_b128 v[180:183], v5 offset:1376
	ds_read_b128 v[184:187], v5 offset:1392
	ds_read_b128 v[188:191], v5 offset:1408
	ds_read_b32 v194, v5 offset:1424
	s_waitcnt vmcnt(16) lgkmcnt(10)
	v_pk_fma_f32 v[16:17], v[110:111], v[144:145], v[16:17] op_sel_hi:[0,1,1]
	v_pk_fma_f32 v[18:19], v[110:111], v[146:147], v[18:19] op_sel_hi:[0,1,1]
	v_pk_fma_f32 v[20:21], v[110:111], v[148:149], v[20:21] op_sel_hi:[0,1,1]
	v_pk_fma_f32 v[22:23], v[110:111], v[150:151], v[22:23] op_sel_hi:[0,1,1]
	v_pk_fma_f32 v[24:25], v[110:111], v[152:153], v[24:25] op_sel_hi:[0,1,1]
	v_pk_fma_f32 v[26:27], v[110:111], v[154:155], v[26:27] op_sel_hi:[0,1,1]
	v_pk_fma_f32 v[28:29], v[110:111], v[156:157], v[28:29] op_sel_hi:[0,1,1]
	v_pk_fma_f32 v[30:31], v[110:111], v[158:159], v[30:31] op_sel_hi:[0,1,1]
	v_fmac_f32_e32 v2, v110, v192
	ds_read_b128 v[144:147], v5 offset:1440
	ds_read_b128 v[148:151], v5 offset:1456
	ds_read_b128 v[152:155], v5 offset:1472
	ds_read_b128 v[156:159], v5 offset:1488
	ds_read_b32 v192, v5 offset:1504
	s_waitcnt vmcnt(15) lgkmcnt(10)
	v_pk_fma_f32 v[16:17], v[112:113], v[160:161], v[16:17] op_sel_hi:[0,1,1]
	v_pk_fma_f32 v[18:19], v[112:113], v[162:163], v[18:19] op_sel_hi:[0,1,1]
	v_pk_fma_f32 v[20:21], v[112:113], v[164:165], v[20:21] op_sel_hi:[0,1,1]
	v_pk_fma_f32 v[22:23], v[112:113], v[166:167], v[22:23] op_sel_hi:[0,1,1]
	v_pk_fma_f32 v[24:25], v[112:113], v[168:169], v[24:25] op_sel_hi:[0,1,1]
	v_pk_fma_f32 v[26:27], v[112:113], v[170:171], v[26:27] op_sel_hi:[0,1,1]
	v_pk_fma_f32 v[28:29], v[112:113], v[172:173], v[28:29] op_sel_hi:[0,1,1]
	v_pk_fma_f32 v[30:31], v[112:113], v[174:175], v[30:31] op_sel_hi:[0,1,1]
	v_fmac_f32_e32 v2, v112, v193
	ds_read_b128 v[160:163], v5 offset:1520
	ds_read_b128 v[164:167], v5 offset:1536
	ds_read_b128 v[168:171], v5 offset:1552
	ds_read_b128 v[172:175], v5 offset:1568
	ds_read_b32 v193, v5 offset:1584
	s_waitcnt vmcnt(14) lgkmcnt(10)
	v_pk_fma_f32 v[16:17], v[114:115], v[176:177], v[16:17] op_sel_hi:[0,1,1]
	v_pk_fma_f32 v[18:19], v[114:115], v[178:179], v[18:19] op_sel_hi:[0,1,1]
	v_pk_fma_f32 v[20:21], v[114:115], v[180:181], v[20:21] op_sel_hi:[0,1,1]
	v_pk_fma_f32 v[22:23], v[114:115], v[182:183], v[22:23] op_sel_hi:[0,1,1]
	v_pk_fma_f32 v[24:25], v[114:115], v[184:185], v[24:25] op_sel_hi:[0,1,1]
	v_pk_fma_f32 v[26:27], v[114:115], v[186:187], v[26:27] op_sel_hi:[0,1,1]
	v_pk_fma_f32 v[28:29], v[114:115], v[188:189], v[28:29] op_sel_hi:[0,1,1]
	v_pk_fma_f32 v[30:31], v[114:115], v[190:191], v[30:31] op_sel_hi:[0,1,1]
	v_fmac_f32_e32 v2, v114, v194
	ds_read_b128 v[176:179], v5 offset:1600
	ds_read_b128 v[180:183], v5 offset:1616
	ds_read_b128 v[184:187], v5 offset:1632
	ds_read_b128 v[188:191], v5 offset:1648
	ds_read_b32 v194, v5 offset:1664
	s_waitcnt vmcnt(13) lgkmcnt(10)
	v_pk_fma_f32 v[16:17], v[116:117], v[144:145], v[16:17] op_sel_hi:[0,1,1]
	v_pk_fma_f32 v[18:19], v[116:117], v[146:147], v[18:19] op_sel_hi:[0,1,1]
	v_pk_fma_f32 v[20:21], v[116:117], v[148:149], v[20:21] op_sel_hi:[0,1,1]
	v_pk_fma_f32 v[22:23], v[116:117], v[150:151], v[22:23] op_sel_hi:[0,1,1]
	v_pk_fma_f32 v[24:25], v[116:117], v[152:153], v[24:25] op_sel_hi:[0,1,1]
	v_pk_fma_f32 v[26:27], v[116:117], v[154:155], v[26:27] op_sel_hi:[0,1,1]
	v_pk_fma_f32 v[28:29], v[116:117], v[156:157], v[28:29] op_sel_hi:[0,1,1]
	v_pk_fma_f32 v[30:31], v[116:117], v[158:159], v[30:31] op_sel_hi:[0,1,1]
	v_fmac_f32_e32 v2, v116, v192
	ds_read_b128 v[144:147], v5 offset:1680
	ds_read_b128 v[148:151], v5 offset:1696
	ds_read_b128 v[152:155], v5 offset:1712
	ds_read_b128 v[156:159], v5 offset:1728
	ds_read_b32 v192, v5 offset:1744
	s_waitcnt vmcnt(12) lgkmcnt(10)
	v_pk_fma_f32 v[16:17], v[118:119], v[160:161], v[16:17] op_sel_hi:[0,1,1]
	v_pk_fma_f32 v[18:19], v[118:119], v[162:163], v[18:19] op_sel_hi:[0,1,1]
	v_pk_fma_f32 v[20:21], v[118:119], v[164:165], v[20:21] op_sel_hi:[0,1,1]
	v_pk_fma_f32 v[22:23], v[118:119], v[166:167], v[22:23] op_sel_hi:[0,1,1]
	v_pk_fma_f32 v[24:25], v[118:119], v[168:169], v[24:25] op_sel_hi:[0,1,1]
	v_pk_fma_f32 v[26:27], v[118:119], v[170:171], v[26:27] op_sel_hi:[0,1,1]
	v_pk_fma_f32 v[28:29], v[118:119], v[172:173], v[28:29] op_sel_hi:[0,1,1]
	v_pk_fma_f32 v[30:31], v[118:119], v[174:175], v[30:31] op_sel_hi:[0,1,1]
	v_fmac_f32_e32 v2, v118, v193
	ds_read_b128 v[160:163], v5 offset:1760
	ds_read_b128 v[164:167], v5 offset:1776
	ds_read_b128 v[168:171], v5 offset:1792
	ds_read_b128 v[172:175], v5 offset:1808
	ds_read_b32 v193, v5 offset:1824
	s_waitcnt vmcnt(11) lgkmcnt(10)
	v_pk_fma_f32 v[16:17], v[120:121], v[176:177], v[16:17] op_sel_hi:[0,1,1]
	v_pk_fma_f32 v[18:19], v[120:121], v[178:179], v[18:19] op_sel_hi:[0,1,1]
	v_pk_fma_f32 v[20:21], v[120:121], v[180:181], v[20:21] op_sel_hi:[0,1,1]
	v_pk_fma_f32 v[22:23], v[120:121], v[182:183], v[22:23] op_sel_hi:[0,1,1]
	v_pk_fma_f32 v[24:25], v[120:121], v[184:185], v[24:25] op_sel_hi:[0,1,1]
	v_pk_fma_f32 v[26:27], v[120:121], v[186:187], v[26:27] op_sel_hi:[0,1,1]
	v_pk_fma_f32 v[28:29], v[120:121], v[188:189], v[28:29] op_sel_hi:[0,1,1]
	v_pk_fma_f32 v[30:31], v[120:121], v[190:191], v[30:31] op_sel_hi:[0,1,1]
	v_fmac_f32_e32 v2, v120, v194
	ds_read_b128 v[176:179], v5 offset:1840
	ds_read_b128 v[180:183], v5 offset:1856
	ds_read_b128 v[184:187], v5 offset:1872
	ds_read_b128 v[188:191], v5 offset:1888
	ds_read_b32 v194, v5 offset:1904
	s_waitcnt vmcnt(10) lgkmcnt(10)
	v_pk_fma_f32 v[16:17], v[122:123], v[144:145], v[16:17] op_sel_hi:[0,1,1]
	v_pk_fma_f32 v[18:19], v[122:123], v[146:147], v[18:19] op_sel_hi:[0,1,1]
	v_pk_fma_f32 v[20:21], v[122:123], v[148:149], v[20:21] op_sel_hi:[0,1,1]
	v_pk_fma_f32 v[22:23], v[122:123], v[150:151], v[22:23] op_sel_hi:[0,1,1]
	v_pk_fma_f32 v[24:25], v[122:123], v[152:153], v[24:25] op_sel_hi:[0,1,1]
	v_pk_fma_f32 v[26:27], v[122:123], v[154:155], v[26:27] op_sel_hi:[0,1,1]
	v_pk_fma_f32 v[28:29], v[122:123], v[156:157], v[28:29] op_sel_hi:[0,1,1]
	v_pk_fma_f32 v[30:31], v[122:123], v[158:159], v[30:31] op_sel_hi:[0,1,1]
	v_fmac_f32_e32 v2, v122, v192
	ds_read_b128 v[144:147], v5 offset:1920
	ds_read_b128 v[148:151], v5 offset:1936
	ds_read_b128 v[152:155], v5 offset:1952
	ds_read_b128 v[156:159], v5 offset:1968
	ds_read_b32 v192, v5 offset:1984
	s_waitcnt vmcnt(9) lgkmcnt(10)
	v_pk_fma_f32 v[16:17], v[124:125], v[160:161], v[16:17] op_sel_hi:[0,1,1]
	v_pk_fma_f32 v[18:19], v[124:125], v[162:163], v[18:19] op_sel_hi:[0,1,1]
	v_pk_fma_f32 v[20:21], v[124:125], v[164:165], v[20:21] op_sel_hi:[0,1,1]
	v_pk_fma_f32 v[22:23], v[124:125], v[166:167], v[22:23] op_sel_hi:[0,1,1]
	v_pk_fma_f32 v[24:25], v[124:125], v[168:169], v[24:25] op_sel_hi:[0,1,1]
	v_pk_fma_f32 v[26:27], v[124:125], v[170:171], v[26:27] op_sel_hi:[0,1,1]
	v_pk_fma_f32 v[28:29], v[124:125], v[172:173], v[28:29] op_sel_hi:[0,1,1]
	v_pk_fma_f32 v[30:31], v[124:125], v[174:175], v[30:31] op_sel_hi:[0,1,1]
	v_fmac_f32_e32 v2, v124, v193
	ds_read_b128 v[160:163], v5 offset:2000
	ds_read_b128 v[164:167], v5 offset:2016
	ds_read_b128 v[168:171], v5 offset:2032
	ds_read_b128 v[172:175], v5 offset:2048
	ds_read_b32 v193, v5 offset:2064
	s_waitcnt vmcnt(8) lgkmcnt(10)
	v_pk_fma_f32 v[16:17], v[126:127], v[176:177], v[16:17] op_sel_hi:[0,1,1]
	v_pk_fma_f32 v[18:19], v[126:127], v[178:179], v[18:19] op_sel_hi:[0,1,1]
	v_pk_fma_f32 v[20:21], v[126:127], v[180:181], v[20:21] op_sel_hi:[0,1,1]
	v_pk_fma_f32 v[22:23], v[126:127], v[182:183], v[22:23] op_sel_hi:[0,1,1]
	v_pk_fma_f32 v[24:25], v[126:127], v[184:185], v[24:25] op_sel_hi:[0,1,1]
	v_pk_fma_f32 v[26:27], v[126:127], v[186:187], v[26:27] op_sel_hi:[0,1,1]
	v_pk_fma_f32 v[28:29], v[126:127], v[188:189], v[28:29] op_sel_hi:[0,1,1]
	v_pk_fma_f32 v[30:31], v[126:127], v[190:191], v[30:31] op_sel_hi:[0,1,1]
	v_fmac_f32_e32 v2, v126, v194
	ds_read_b128 v[176:179], v5 offset:2080
	ds_read_b128 v[180:183], v5 offset:2096
	ds_read_b128 v[184:187], v5 offset:2112
	ds_read_b128 v[188:191], v5 offset:2128
	ds_read_b32 v194, v5 offset:2144
	s_waitcnt vmcnt(7) lgkmcnt(10)
	v_pk_fma_f32 v[16:17], v[128:129], v[144:145], v[16:17] op_sel_hi:[0,1,1]
	v_pk_fma_f32 v[18:19], v[128:129], v[146:147], v[18:19] op_sel_hi:[0,1,1]
	v_pk_fma_f32 v[20:21], v[128:129], v[148:149], v[20:21] op_sel_hi:[0,1,1]
	v_pk_fma_f32 v[22:23], v[128:129], v[150:151], v[22:23] op_sel_hi:[0,1,1]
	v_pk_fma_f32 v[24:25], v[128:129], v[152:153], v[24:25] op_sel_hi:[0,1,1]
	v_pk_fma_f32 v[26:27], v[128:129], v[154:155], v[26:27] op_sel_hi:[0,1,1]
	v_pk_fma_f32 v[28:29], v[128:129], v[156:157], v[28:29] op_sel_hi:[0,1,1]
	v_pk_fma_f32 v[30:31], v[128:129], v[158:159], v[30:31] op_sel_hi:[0,1,1]
	v_fmac_f32_e32 v2, v128, v192
	ds_read_b128 v[144:147], v5 offset:2160
	ds_read_b128 v[148:151], v5 offset:2176
	ds_read_b128 v[152:155], v5 offset:2192
	ds_read_b128 v[156:159], v5 offset:2208
	ds_read_b32 v192, v5 offset:2224
	s_waitcnt vmcnt(6) lgkmcnt(10)
	v_pk_fma_f32 v[16:17], v[130:131], v[160:161], v[16:17] op_sel_hi:[0,1,1]
	v_pk_fma_f32 v[18:19], v[130:131], v[162:163], v[18:19] op_sel_hi:[0,1,1]
	v_pk_fma_f32 v[20:21], v[130:131], v[164:165], v[20:21] op_sel_hi:[0,1,1]
	v_pk_fma_f32 v[22:23], v[130:131], v[166:167], v[22:23] op_sel_hi:[0,1,1]
	v_pk_fma_f32 v[24:25], v[130:131], v[168:169], v[24:25] op_sel_hi:[0,1,1]
	v_pk_fma_f32 v[26:27], v[130:131], v[170:171], v[26:27] op_sel_hi:[0,1,1]
	v_pk_fma_f32 v[28:29], v[130:131], v[172:173], v[28:29] op_sel_hi:[0,1,1]
	v_pk_fma_f32 v[30:31], v[130:131], v[174:175], v[30:31] op_sel_hi:[0,1,1]
	v_fmac_f32_e32 v2, v130, v193
	ds_read_b128 v[160:163], v5 offset:2240
	ds_read_b128 v[164:167], v5 offset:2256
	ds_read_b128 v[168:171], v5 offset:2272
	ds_read_b128 v[172:175], v5 offset:2288
	ds_read_b32 v193, v5 offset:2304
	s_waitcnt vmcnt(5) lgkmcnt(10)
	v_pk_fma_f32 v[16:17], v[132:133], v[176:177], v[16:17] op_sel_hi:[0,1,1]
	v_pk_fma_f32 v[18:19], v[132:133], v[178:179], v[18:19] op_sel_hi:[0,1,1]
	v_pk_fma_f32 v[20:21], v[132:133], v[180:181], v[20:21] op_sel_hi:[0,1,1]
	v_pk_fma_f32 v[22:23], v[132:133], v[182:183], v[22:23] op_sel_hi:[0,1,1]
	v_pk_fma_f32 v[24:25], v[132:133], v[184:185], v[24:25] op_sel_hi:[0,1,1]
	v_pk_fma_f32 v[26:27], v[132:133], v[186:187], v[26:27] op_sel_hi:[0,1,1]
	v_pk_fma_f32 v[28:29], v[132:133], v[188:189], v[28:29] op_sel_hi:[0,1,1]
	v_pk_fma_f32 v[30:31], v[132:133], v[190:191], v[30:31] op_sel_hi:[0,1,1]
	v_fmac_f32_e32 v2, v132, v194
	ds_read_b128 v[176:179], v5 offset:2320
	ds_read_b128 v[180:183], v5 offset:2336
	ds_read_b128 v[184:187], v5 offset:2352
	ds_read_b128 v[188:191], v5 offset:2368
	ds_read_b32 v194, v5 offset:2384
	s_waitcnt vmcnt(4) lgkmcnt(10)
	v_pk_fma_f32 v[16:17], v[134:135], v[144:145], v[16:17] op_sel_hi:[0,1,1]
	v_pk_fma_f32 v[18:19], v[134:135], v[146:147], v[18:19] op_sel_hi:[0,1,1]
	v_pk_fma_f32 v[20:21], v[134:135], v[148:149], v[20:21] op_sel_hi:[0,1,1]
	v_pk_fma_f32 v[22:23], v[134:135], v[150:151], v[22:23] op_sel_hi:[0,1,1]
	v_pk_fma_f32 v[24:25], v[134:135], v[152:153], v[24:25] op_sel_hi:[0,1,1]
	v_pk_fma_f32 v[26:27], v[134:135], v[154:155], v[26:27] op_sel_hi:[0,1,1]
	v_pk_fma_f32 v[28:29], v[134:135], v[156:157], v[28:29] op_sel_hi:[0,1,1]
	v_pk_fma_f32 v[30:31], v[134:135], v[158:159], v[30:31] op_sel_hi:[0,1,1]
	v_fmac_f32_e32 v2, v134, v192
	ds_read_b128 v[144:147], v5 offset:2400
	ds_read_b128 v[148:151], v5 offset:2416
	ds_read_b128 v[152:155], v5 offset:2432
	ds_read_b128 v[156:159], v5 offset:2448
	ds_read_b32 v192, v5 offset:2464
	s_waitcnt vmcnt(3) lgkmcnt(10)
	v_pk_fma_f32 v[16:17], v[136:137], v[160:161], v[16:17] op_sel_hi:[0,1,1]
	v_pk_fma_f32 v[18:19], v[136:137], v[162:163], v[18:19] op_sel_hi:[0,1,1]
	v_pk_fma_f32 v[20:21], v[136:137], v[164:165], v[20:21] op_sel_hi:[0,1,1]
	v_pk_fma_f32 v[22:23], v[136:137], v[166:167], v[22:23] op_sel_hi:[0,1,1]
	v_pk_fma_f32 v[24:25], v[136:137], v[168:169], v[24:25] op_sel_hi:[0,1,1]
	v_pk_fma_f32 v[26:27], v[136:137], v[170:171], v[26:27] op_sel_hi:[0,1,1]
	v_pk_fma_f32 v[28:29], v[136:137], v[172:173], v[28:29] op_sel_hi:[0,1,1]
	v_pk_fma_f32 v[30:31], v[136:137], v[174:175], v[30:31] op_sel_hi:[0,1,1]
	v_fmac_f32_e32 v2, v136, v193
	ds_read_b128 v[160:163], v5 offset:2480
	ds_read_b128 v[164:167], v5 offset:2496
	ds_read_b128 v[168:171], v5 offset:2512
	ds_read_b128 v[172:175], v5 offset:2528
	ds_read_b32 v193, v5 offset:2544
	s_waitcnt vmcnt(2) lgkmcnt(10)
	v_pk_fma_f32 v[16:17], v[138:139], v[176:177], v[16:17] op_sel_hi:[0,1,1]
	v_pk_fma_f32 v[18:19], v[138:139], v[178:179], v[18:19] op_sel_hi:[0,1,1]
	v_pk_fma_f32 v[20:21], v[138:139], v[180:181], v[20:21] op_sel_hi:[0,1,1]
	v_pk_fma_f32 v[22:23], v[138:139], v[182:183], v[22:23] op_sel_hi:[0,1,1]
	v_pk_fma_f32 v[24:25], v[138:139], v[184:185], v[24:25] op_sel_hi:[0,1,1]
	v_pk_fma_f32 v[26:27], v[138:139], v[186:187], v[26:27] op_sel_hi:[0,1,1]
	v_pk_fma_f32 v[28:29], v[138:139], v[188:189], v[28:29] op_sel_hi:[0,1,1]
	v_pk_fma_f32 v[30:31], v[138:139], v[190:191], v[30:31] op_sel_hi:[0,1,1]
	v_fmac_f32_e32 v2, v138, v194
	s_waitcnt vmcnt(1) lgkmcnt(5)
	v_pk_fma_f32 v[16:17], v[140:141], v[144:145], v[16:17] op_sel_hi:[0,1,1]
	v_pk_fma_f32 v[18:19], v[140:141], v[146:147], v[18:19] op_sel_hi:[0,1,1]
	v_pk_fma_f32 v[20:21], v[140:141], v[148:149], v[20:21] op_sel_hi:[0,1,1]
	v_pk_fma_f32 v[22:23], v[140:141], v[150:151], v[22:23] op_sel_hi:[0,1,1]
	v_pk_fma_f32 v[24:25], v[140:141], v[152:153], v[24:25] op_sel_hi:[0,1,1]
	v_pk_fma_f32 v[26:27], v[140:141], v[154:155], v[26:27] op_sel_hi:[0,1,1]
	v_pk_fma_f32 v[28:29], v[140:141], v[156:157], v[28:29] op_sel_hi:[0,1,1]
	v_pk_fma_f32 v[30:31], v[140:141], v[158:159], v[30:31] op_sel_hi:[0,1,1]
	v_fmac_f32_e32 v2, v140, v192
	s_waitcnt vmcnt(0) lgkmcnt(0)
	v_pk_fma_f32 v[16:17], v[142:143], v[160:161], v[16:17] op_sel_hi:[0,1,1]
	v_pk_fma_f32 v[18:19], v[142:143], v[162:163], v[18:19] op_sel_hi:[0,1,1]
	v_pk_fma_f32 v[20:21], v[142:143], v[164:165], v[20:21] op_sel_hi:[0,1,1]
	v_pk_fma_f32 v[22:23], v[142:143], v[166:167], v[22:23] op_sel_hi:[0,1,1]
	v_pk_fma_f32 v[24:25], v[142:143], v[168:169], v[24:25] op_sel_hi:[0,1,1]
	v_pk_fma_f32 v[26:27], v[142:143], v[170:171], v[26:27] op_sel_hi:[0,1,1]
	v_pk_fma_f32 v[28:29], v[142:143], v[172:173], v[28:29] op_sel_hi:[0,1,1]
	v_pk_fma_f32 v[30:31], v[142:143], v[174:175], v[30:31] op_sel_hi:[0,1,1]
	v_fmac_f32_e32 v2, v142, v193
	s_cmpk_eq_i32 s1, 0x80
	s_cbranch_scc0 .LBB0_19
	s_movk_i32 s1, 0x440
	v_lshl_add_u32 v5, v4, 2, s37
	v_cmp_gt_i32_e32 vcc, s1, v8
	ds_write2st64_b32 v5, v16, v17 offset1:1
	ds_write2st64_b32 v5, v18, v19 offset0:2 offset1:3
	ds_write2st64_b32 v5, v20, v21 offset0:4 offset1:5
	ds_write2st64_b32 v5, v22, v23 offset0:6 offset1:7
	ds_write2st64_b32 v5, v24, v25 offset0:8 offset1:9
	ds_write2st64_b32 v5, v26, v27 offset0:10 offset1:11
	ds_write2st64_b32 v5, v28, v29 offset0:12 offset1:13
	ds_write2st64_b32 v5, v30, v31 offset0:14 offset1:15
	ds_write_b32 v5, v2 offset:4096
	s_waitcnt lgkmcnt(0)
	s_barrier
	s_and_saveexec_b64 s[8:9], vcc
	s_cbranch_execz .LBB0_5
	s_mul_i32 s1, s0, 0x1800
	s_add_i32 s6, s1, s2
	v_and_b32_e32 v7, 63, v4
	s_add_u32 s2, s20, s4
	v_or_b32_e32 v14, s6, v7
	v_readlane_b32 s64, v239, 44
	s_addc_u32 s3, s21, s5
	v_lshlrev_b32_e32 v2, 2, v7
	v_ashrrev_i32_e32 v15, 31, v14
	v_readlane_b32 s74, v239, 54
	v_readlane_b32 s75, v239, 55
	s_mul_hi_i32 s1, s0, 17
	s_mul_i32 s0, s0, 17
	v_or_b32_e32 v5, 0x14000, v2
	v_lshl_add_u64 v[14:15], v[14:15], 2, s[74:75]
	v_lshl_add_u64 v[16:17], s[2:3], 0, v[2:3]
	s_mov_b64 s[2:3], 0
	v_mov_b32_e32 v2, v8
	v_readlane_b32 s65, v239, 45
	v_readlane_b32 s66, v239, 46
	v_readlane_b32 s67, v239, 47
	v_readlane_b32 s68, v239, 48
	v_readlane_b32 s69, v239, 49
	v_readlane_b32 s70, v239, 50
	v_readlane_b32 s71, v239, 51
	v_readlane_b32 s72, v239, 52
	v_readlane_b32 s73, v239, 53
	v_readlane_b32 s76, v239, 56
	v_readlane_b32 s77, v239, 57
	v_readlane_b32 s78, v239, 58
	v_readlane_b32 s79, v239, 59

.LBB0_24:
	s_and_b32 s46, s47, 0xfc0
	s_lshl_b32 s1, s46, 2
	v_readlane_b32 s48, v239, 0
	v_readlane_b32 s49, v239, 1
	s_add_u32 s6, s48, s1
	s_addc_u32 s7, s49, 0
	v_mov_b32_e32 v7, v3
	v_lshl_add_u64 v[14:15], s[6:7], 0, v[6:7]
	v_mad_u64_u32 v[16:17], s[6:7], s12, v38, v[14:15]
	s_barrier
	global_load_dword v240, v[16:17], off
	v_mad_u64_u32 v[16:17], s[4:5], s4, v38, v[14:15]
	v_readlane_b32 s50, v239, 2
	v_readlane_b32 s51, v239, 3
	v_readlane_b32 s52, v239, 4
	v_readlane_b32 s53, v239, 5
	v_readlane_b32 s54, v239, 6
	v_readlane_b32 s55, v239, 7
	v_readlane_b32 s56, v239, 8
	v_readlane_b32 s57, v239, 9
	v_readlane_b32 s58, v239, 10
	v_readlane_b32 s59, v239, 11
	v_readlane_b32 s60, v239, 12
	v_readlane_b32 s61, v239, 13
	v_readlane_b32 s62, v239, 14
	v_readlane_b32 s63, v239, 15
	global_load_dword v241, v[16:17], off
	v_mad_u64_u32 v[16:17], s[2:3], s2, v38, v[14:15]
	global_load_dword v242, v[16:17], off
	v_mad_u64_u32 v[16:17], s[0:1], s0, v38, v[14:15]
	s_add_i32 s0, s45, s11
	global_load_dword v243, v[16:17], off
	v_mad_u64_u32 v[16:17], s[0:1], s0, v38, v[14:15]
	s_add_i32 s0, s45, s33
	global_load_dword v244, v[16:17], off
	v_mad_u64_u32 v[16:17], s[0:1], s0, v38, v[14:15]
	s_add_i32 s0, s45, s34
	global_load_dword v245, v[16:17], off
	v_mad_u64_u32 v[16:17], s[0:1], s0, v38, v[14:15]
	s_add_i32 s0, s45, s35
	s_nop 0
	v_mad_u64_u32 v[14:15], s[0:1], s0, v38, v[14:15]
	global_load_dword v246, v[16:17], off
	global_load_dword v247, v[14:15], off
	s_waitcnt vmcnt(7)
	ds_write_b32 v37, v240
	s_waitcnt vmcnt(6)
	ds_write_b32 v37, v241 offset:2080
	s_waitcnt vmcnt(5)
	ds_write_b32 v37, v242 offset:4160
	s_waitcnt vmcnt(4)
	ds_write_b32 v37, v243 offset:6240
	s_waitcnt vmcnt(3)
	ds_write_b32 v37, v244 offset:8320
	s_waitcnt vmcnt(2)
	ds_write_b32 v37, v245 offset:10400
	s_waitcnt vmcnt(1)
	ds_write_b32 v37, v246 offset:12480
	s_waitcnt vmcnt(0)
	ds_write_b32 v37, v247 offset:14560
	s_waitcnt lgkmcnt(0)
	s_barrier
